# static priority raise strategy, other half: s_setprio 1 for waves 0-3 on entry to the SSD chunk loop path
# baseline (speedup 1.0000x reference)
; __device__ __forceinline__ void phaseC(const Params& p, const int wv, const int r0, const int r1, const int r2, const int r3, const int r4, unsigned* bar) {
;     ...
;   if ((int)blockIdx.x < nS) {
;     for (int it = blockIdx.x; it < 128 * r0; it += nS) ssd_prompt_item(p, it & 127, wv);
.LBB0_562:
	s_and_b64 vcc, exec, s[0:1]
	s_cbranch_vccz .LBB0_633
	s_lshl_b32 s1, s56, 7
	v_readlane_b32 s0, v251, 0
	s_cmp_ge_i32 s0, s1
	v_writelane_b32 v250, s1, 4
	s_cbranch_scc1 .LBB0_633
	s_cmp_ge_u32 s83, 4
	s_cbranch_scc1 .Lprio_c
	s_setprio 1
